# conformer conv31 chain: LDS reads software-pipelined with counted lgkmcnt(1) waits
# speedup vs baseline: 1.0041x; 1.0041x over previous
; #define LAS __attribute__((address_space(3)))
;     static __device__ __forceinline__ void run(float (&acc)[32], const float (&w)[31], const LAS float* us) {
;         const float v = us[J * 512];
;         constexpr int TLO = (J - 30 > 0) ? J - 30 : 0, THI = (J < 31) ? J : 31;
; #pragma unroll
;         for (int t = TLO; t <= THI; ++t) acc[t] += v * w[J - t];
;         if constexpr (J + 1 < 62) CfLds<J + 1>::run(acc, w, us);
;     }
; __device__ __forceinline__ void cf_prompt_items(LAS unsigned char* lds, const bf16_t* PROJ, int it0, int itstride, int nitems, const float* cw, const float* cb, bf16_t* CONVOUT, float* pcfc) {
;     ...
;         float acc[32];
; #pragma unroll
;         for (int t = 0; t < 32; ++t) acc[t] = bias;
;         CfLds<0>::run(acc, wv, Us + tid);
.LBB0_242:
	ds_read2st64_b32 v[144:145], v52 offset1:8
	s_and_b32 s82, s75, 0xffffffe0
	s_lshl_b32 s38, s83, 1
	s_ashr_i32 s83, s82, 31
	s_lshl_b64 s[0:1], s[82:83], 12
	ds_read2st64_b32 v[14:15], v52 offset0:16 offset1:24
	s_waitcnt vmcnt(0) lgkmcnt(1)
	v_fma_f32 v36, v143, v144, v91
	v_fmac_f32_e32 v36, v142, v145
	v_fma_f32 v13, v143, v145, v91
	s_andn2_b64 vcc, exec, s[80:81]
	s_mov_b32 s33, s93
	ds_read2st64_b32 v[144:145], v52 offset0:32 offset1:40
	s_waitcnt lgkmcnt(1)
	v_fmac_f32_e32 v36, v141, v14
	v_fmac_f32_e32 v13, v142, v14
	v_fma_f32 v38, v143, v14, v91
	v_fmac_f32_e32 v36, v140, v15
	v_fmac_f32_e32 v13, v141, v15
	v_fmac_f32_e32 v38, v142, v15
	v_fma_f32 v37, v143, v15, v91
	ds_read2st64_b32 v[14:15], v52 offset0:48 offset1:56
	s_waitcnt lgkmcnt(1)
	v_fmac_f32_e32 v36, v139, v144
	v_fmac_f32_e32 v13, v140, v144
	v_fmac_f32_e32 v38, v141, v144
	v_fmac_f32_e32 v37, v142, v144
	v_fma_f32 v40, v143, v144, v91
	v_fmac_f32_e32 v36, v138, v145
	v_fmac_f32_e32 v13, v139, v145
	v_fmac_f32_e32 v38, v140, v145
	v_fmac_f32_e32 v37, v141, v145
	v_fmac_f32_e32 v40, v142, v145
	v_fma_f32 v39, v143, v145, v91
	ds_read2st64_b32 v[144:145], v52 offset0:64 offset1:72
	s_waitcnt lgkmcnt(1)
	v_fmac_f32_e32 v36, v137, v14
	v_fmac_f32_e32 v13, v138, v14
	v_fmac_f32_e32 v38, v139, v14
	v_fmac_f32_e32 v37, v140, v14
	v_fmac_f32_e32 v40, v141, v14
	v_fmac_f32_e32 v39, v142, v14
	v_fma_f32 v41, v143, v14, v91
	v_fmac_f32_e32 v36, v136, v15
	v_fmac_f32_e32 v13, v137, v15
	v_fmac_f32_e32 v38, v138, v15
	v_fmac_f32_e32 v37, v139, v15
	v_fmac_f32_e32 v40, v140, v15
	v_fmac_f32_e32 v39, v141, v15
	v_fmac_f32_e32 v41, v142, v15
	v_fma_f32 v42, v143, v15, v91
	ds_read2st64_b32 v[14:15], v52 offset0:80 offset1:88
	s_waitcnt lgkmcnt(1)
	v_fmac_f32_e32 v36, v127, v144
	v_fmac_f32_e32 v13, v136, v144
	v_fmac_f32_e32 v38, v137, v144
	v_fmac_f32_e32 v37, v138, v144
	v_fmac_f32_e32 v40, v139, v144
	v_fmac_f32_e32 v39, v140, v144
	v_fmac_f32_e32 v41, v141, v144
	v_fmac_f32_e32 v42, v142, v144
	v_fma_f32 v43, v143, v144, v91
	v_fmac_f32_e32 v36, v126, v145
	v_fmac_f32_e32 v13, v127, v145
	v_fmac_f32_e32 v38, v136, v145
	v_fmac_f32_e32 v37, v137, v145
	v_fmac_f32_e32 v40, v138, v145
	v_fmac_f32_e32 v39, v139, v145
	v_fmac_f32_e32 v41, v140, v145
	v_fmac_f32_e32 v42, v141, v145
	v_fmac_f32_e32 v43, v142, v145
	v_fma_f32 v47, v143, v145, v91
	ds_read2st64_b32 v[144:145], v52 offset0:96 offset1:104
	s_waitcnt lgkmcnt(1)
	v_fmac_f32_e32 v36, v123, v14
	v_fmac_f32_e32 v13, v126, v14
	v_fmac_f32_e32 v38, v127, v14
	v_fmac_f32_e32 v37, v136, v14
	v_fmac_f32_e32 v40, v137, v14
	v_fmac_f32_e32 v39, v138, v14
	v_fmac_f32_e32 v41, v139, v14
	v_fmac_f32_e32 v42, v140, v14
	v_fmac_f32_e32 v43, v141, v14
	v_fmac_f32_e32 v47, v142, v14
	v_fma_f32 v107, v143, v14, v91
	v_fmac_f32_e32 v36, v120, v15
	v_fmac_f32_e32 v13, v123, v15
	v_fmac_f32_e32 v38, v126, v15
	v_fmac_f32_e32 v37, v127, v15
	v_fmac_f32_e32 v40, v136, v15
	v_fmac_f32_e32 v39, v137, v15
	v_fmac_f32_e32 v41, v138, v15
	v_fmac_f32_e32 v42, v139, v15
	v_fmac_f32_e32 v43, v140, v15
	v_fmac_f32_e32 v47, v141, v15
	v_fmac_f32_e32 v107, v142, v15
	v_fma_f32 v109, v143, v15, v91
	ds_read2st64_b32 v[14:15], v52 offset0:112 offset1:120
	s_waitcnt lgkmcnt(1)
	v_fmac_f32_e32 v36, v117, v144
	v_fmac_f32_e32 v13, v120, v144
	v_fmac_f32_e32 v38, v123, v144
	v_fmac_f32_e32 v37, v126, v144
	v_fmac_f32_e32 v40, v127, v144
	v_fmac_f32_e32 v39, v136, v144
	v_fmac_f32_e32 v41, v137, v144
	v_fmac_f32_e32 v42, v138, v144
	v_fmac_f32_e32 v43, v139, v144
	v_fmac_f32_e32 v47, v140, v144
	v_fmac_f32_e32 v107, v141, v144
	v_fmac_f32_e32 v109, v142, v144
	v_fma_f32 v110, v143, v144, v91
	v_fmac_f32_e32 v36, v114, v145
	v_fmac_f32_e32 v13, v117, v145
	v_fmac_f32_e32 v38, v120, v145
	v_fmac_f32_e32 v37, v123, v145
	v_fmac_f32_e32 v40, v126, v145
	v_fmac_f32_e32 v39, v127, v145
	v_fmac_f32_e32 v41, v136, v145
	v_fmac_f32_e32 v42, v137, v145
	v_fmac_f32_e32 v43, v138, v145
	v_fmac_f32_e32 v47, v139, v145
	v_fmac_f32_e32 v107, v140, v145
	v_fmac_f32_e32 v109, v141, v145
	v_fmac_f32_e32 v110, v142, v145
	v_fma_f32 v112, v143, v145, v91
	ds_read2st64_b32 v[144:145], v52 offset0:128 offset1:136
	s_waitcnt lgkmcnt(1)
	v_fmac_f32_e32 v36, v111, v14
	v_fmac_f32_e32 v13, v114, v14
	v_fmac_f32_e32 v38, v117, v14
	v_fmac_f32_e32 v37, v120, v14
	v_fmac_f32_e32 v40, v123, v14
	v_fmac_f32_e32 v39, v126, v14
	v_fmac_f32_e32 v41, v127, v14
	v_fmac_f32_e32 v42, v136, v14
	v_fmac_f32_e32 v43, v137, v14
	v_fmac_f32_e32 v47, v138, v14
	v_fmac_f32_e32 v107, v139, v14
	v_fmac_f32_e32 v109, v140, v14
	v_fmac_f32_e32 v110, v141, v14
	v_fmac_f32_e32 v112, v142, v14
	v_fma_f32 v113, v143, v14, v91
	v_fmac_f32_e32 v36, v108, v15
	v_fmac_f32_e32 v13, v111, v15
	v_fmac_f32_e32 v38, v114, v15
	v_fmac_f32_e32 v37, v117, v15
	v_fmac_f32_e32 v40, v120, v15
	v_fmac_f32_e32 v39, v123, v15
	v_fmac_f32_e32 v41, v126, v15
	v_fmac_f32_e32 v42, v127, v15
	v_fmac_f32_e32 v43, v136, v15
	v_fmac_f32_e32 v47, v137, v15
	v_fmac_f32_e32 v107, v138, v15
	v_fmac_f32_e32 v109, v139, v15
	v_fmac_f32_e32 v110, v140, v15
	v_fmac_f32_e32 v112, v141, v15
	v_fmac_f32_e32 v113, v142, v15
	v_fma_f32 v115, v143, v15, v91
	ds_read2st64_b32 v[14:15], v52 offset0:144 offset1:152
	s_waitcnt lgkmcnt(1)
; #define LAS __attribute__((address_space(3)))
;     static __device__ __forceinline__ void run(float (&acc)[32], const float (&w)[31], const LAS float* us) {
;         const float v = us[J * 512];
;         constexpr int TLO = (J - 30 > 0) ? J - 30 : 0, THI = (J < 31) ? J : 31;
; #pragma unroll
;         for (int t = TLO; t <= THI; ++t) acc[t] += v * w[J - t];
;         if constexpr (J + 1 < 62) CfLds<J + 1>::run(acc, w, us);
;     }
	v_fmac_f32_e32 v36, v106, v144
	v_fmac_f32_e32 v13, v108, v144
	v_fmac_f32_e32 v38, v111, v144
	v_fmac_f32_e32 v37, v114, v144
	v_fmac_f32_e32 v40, v117, v144
	v_fmac_f32_e32 v39, v120, v144
	v_fmac_f32_e32 v41, v123, v144
	v_fmac_f32_e32 v42, v126, v144
	v_fmac_f32_e32 v43, v127, v144
	v_fmac_f32_e32 v47, v136, v144
	v_fmac_f32_e32 v107, v137, v144
	v_fmac_f32_e32 v109, v138, v144
	v_fmac_f32_e32 v110, v139, v144
	v_fmac_f32_e32 v112, v140, v144
	v_fmac_f32_e32 v113, v141, v144
	v_fmac_f32_e32 v115, v142, v144
	v_fma_f32 v116, v143, v144, v91
	v_fmac_f32_e32 v36, v105, v145
	v_fmac_f32_e32 v13, v106, v145
	v_fmac_f32_e32 v38, v108, v145
	v_fmac_f32_e32 v37, v111, v145
	v_fmac_f32_e32 v40, v114, v145
	v_fmac_f32_e32 v39, v117, v145
	v_fmac_f32_e32 v41, v120, v145
	v_fmac_f32_e32 v42, v123, v145
	v_fmac_f32_e32 v43, v126, v145
	v_fmac_f32_e32 v47, v127, v145
	v_fmac_f32_e32 v107, v136, v145
	v_fmac_f32_e32 v109, v137, v145
	v_fmac_f32_e32 v110, v138, v145
	v_fmac_f32_e32 v112, v139, v145
	v_fmac_f32_e32 v113, v140, v145
	v_fmac_f32_e32 v115, v141, v145
	v_fmac_f32_e32 v116, v142, v145
	v_fma_f32 v118, v143, v145, v91
	ds_read2st64_b32 v[144:145], v52 offset0:160 offset1:168
	s_waitcnt lgkmcnt(1)
	v_fmac_f32_e32 v36, v104, v14
	v_fmac_f32_e32 v13, v105, v14
	v_fmac_f32_e32 v38, v106, v14
	v_fmac_f32_e32 v37, v108, v14
	v_fmac_f32_e32 v40, v111, v14
	v_fmac_f32_e32 v39, v114, v14
	v_fmac_f32_e32 v41, v117, v14
	v_fmac_f32_e32 v42, v120, v14
	v_fmac_f32_e32 v43, v123, v14
	v_fmac_f32_e32 v47, v126, v14
	v_fmac_f32_e32 v107, v127, v14
	v_fmac_f32_e32 v109, v136, v14
	v_fmac_f32_e32 v110, v137, v14
	v_fmac_f32_e32 v112, v138, v14
	v_fmac_f32_e32 v113, v139, v14
	v_fmac_f32_e32 v115, v140, v14
	v_fmac_f32_e32 v116, v141, v14
	v_fmac_f32_e32 v118, v142, v14
	v_fma_f32 v119, v143, v14, v91
	v_fmac_f32_e32 v36, v103, v15
	v_fmac_f32_e32 v13, v104, v15
	v_fmac_f32_e32 v38, v105, v15
	v_fmac_f32_e32 v37, v106, v15
	v_fmac_f32_e32 v40, v108, v15
	v_fmac_f32_e32 v39, v111, v15
	v_fmac_f32_e32 v41, v114, v15
	v_fmac_f32_e32 v42, v117, v15
	v_fmac_f32_e32 v43, v120, v15
	v_fmac_f32_e32 v47, v123, v15
	v_fmac_f32_e32 v107, v126, v15
	v_fmac_f32_e32 v109, v127, v15
	v_fmac_f32_e32 v110, v136, v15
	v_fmac_f32_e32 v112, v137, v15
	v_fmac_f32_e32 v113, v138, v15
	v_fmac_f32_e32 v115, v139, v15
	v_fmac_f32_e32 v116, v140, v15
	v_fmac_f32_e32 v118, v141, v15
	v_fmac_f32_e32 v119, v142, v15
	v_fma_f32 v121, v143, v15, v91
	ds_read2st64_b32 v[14:15], v52 offset0:176 offset1:184
	s_waitcnt lgkmcnt(1)
	v_fmac_f32_e32 v36, v102, v144
	v_fmac_f32_e32 v13, v103, v144
	v_fmac_f32_e32 v38, v104, v144
	v_fmac_f32_e32 v37, v105, v144
	v_fmac_f32_e32 v40, v106, v144
	v_fmac_f32_e32 v39, v108, v144
	v_fmac_f32_e32 v41, v111, v144
	v_fmac_f32_e32 v42, v114, v144
	v_fmac_f32_e32 v43, v117, v144
	v_fmac_f32_e32 v47, v120, v144
	v_fmac_f32_e32 v107, v123, v144
	v_fmac_f32_e32 v109, v126, v144
	v_fmac_f32_e32 v110, v127, v144
	v_fmac_f32_e32 v112, v136, v144
	v_fmac_f32_e32 v113, v137, v144
	v_fmac_f32_e32 v115, v138, v144
	v_fmac_f32_e32 v116, v139, v144
	v_fmac_f32_e32 v118, v140, v144
	v_fmac_f32_e32 v119, v141, v144
	v_fmac_f32_e32 v121, v142, v144
	v_fma_f32 v122, v143, v144, v91
	v_fmac_f32_e32 v36, v101, v145
	v_fmac_f32_e32 v13, v102, v145
	v_fmac_f32_e32 v38, v103, v145
	v_fmac_f32_e32 v37, v104, v145
	v_fmac_f32_e32 v40, v105, v145
	v_fmac_f32_e32 v39, v106, v145
	v_fmac_f32_e32 v41, v108, v145
	v_fmac_f32_e32 v42, v111, v145
	v_fmac_f32_e32 v43, v114, v145
	v_fmac_f32_e32 v47, v117, v145
	v_fmac_f32_e32 v107, v120, v145
	v_fmac_f32_e32 v109, v123, v145
	v_fmac_f32_e32 v110, v126, v145
	v_fmac_f32_e32 v112, v127, v145
	v_fmac_f32_e32 v113, v136, v145
	v_fmac_f32_e32 v115, v137, v145
	v_fmac_f32_e32 v116, v138, v145
	v_fmac_f32_e32 v118, v139, v145
	v_fmac_f32_e32 v119, v140, v145
	v_fmac_f32_e32 v121, v141, v145
	v_fmac_f32_e32 v122, v142, v145
	v_fma_f32 v124, v143, v145, v91
	ds_read2st64_b32 v[144:145], v52 offset0:192 offset1:200
	s_waitcnt lgkmcnt(1)
	v_fmac_f32_e32 v36, v100, v14
	v_fmac_f32_e32 v13, v101, v14
	v_fmac_f32_e32 v38, v102, v14
	v_fmac_f32_e32 v37, v103, v14
	v_fmac_f32_e32 v40, v104, v14
	v_fmac_f32_e32 v39, v105, v14
	v_fmac_f32_e32 v41, v106, v14
	v_fmac_f32_e32 v42, v108, v14
	v_fmac_f32_e32 v43, v111, v14
	v_fmac_f32_e32 v47, v114, v14
	v_fmac_f32_e32 v107, v117, v14
	v_fmac_f32_e32 v109, v120, v14
	v_fmac_f32_e32 v110, v123, v14
	v_fmac_f32_e32 v112, v126, v14
	v_fmac_f32_e32 v113, v127, v14
	v_fmac_f32_e32 v115, v136, v14
	v_fmac_f32_e32 v116, v137, v14
	v_fmac_f32_e32 v118, v138, v14
	v_fmac_f32_e32 v119, v139, v14
	v_fmac_f32_e32 v121, v140, v14
	v_fmac_f32_e32 v122, v141, v14
	v_fmac_f32_e32 v124, v142, v14
	v_fma_f32 v125, v143, v14, v91
	v_fmac_f32_e32 v36, v99, v15
	v_fmac_f32_e32 v13, v100, v15
	v_fmac_f32_e32 v38, v101, v15
	v_fmac_f32_e32 v37, v102, v15
	v_fmac_f32_e32 v40, v103, v15
	v_fmac_f32_e32 v39, v104, v15
	v_fmac_f32_e32 v41, v105, v15
	v_fmac_f32_e32 v42, v106, v15
	v_fmac_f32_e32 v43, v108, v15
	v_fmac_f32_e32 v47, v111, v15
	v_fmac_f32_e32 v107, v114, v15
	v_fmac_f32_e32 v109, v117, v15
	v_fmac_f32_e32 v110, v120, v15
	v_fmac_f32_e32 v112, v123, v15
	v_fmac_f32_e32 v113, v126, v15
	v_fmac_f32_e32 v115, v127, v15
	v_fmac_f32_e32 v116, v136, v15
	v_fmac_f32_e32 v118, v137, v15
	v_fmac_f32_e32 v119, v138, v15
	v_fmac_f32_e32 v121, v139, v15
	v_fmac_f32_e32 v122, v140, v15
	v_fmac_f32_e32 v124, v141, v15
	v_fmac_f32_e32 v125, v142, v15
	v_fma_f32 v128, v143, v15, v91
	ds_read2st64_b32 v[14:15], v52 offset0:208 offset1:216
	s_waitcnt lgkmcnt(1)
; #define LAS __attribute__((address_space(3)))
;     static __device__ __forceinline__ void run(float (&acc)[32], const float (&w)[31], const LAS float* us) {
;         const float v = us[J * 512];
;         constexpr int TLO = (J - 30 > 0) ? J - 30 : 0, THI = (J < 31) ? J : 31;
; #pragma unroll
;         for (int t = TLO; t <= THI; ++t) acc[t] += v * w[J - t];
;         if constexpr (J + 1 < 62) CfLds<J + 1>::run(acc, w, us);
;     }
	v_fmac_f32_e32 v36, v98, v144
	v_fmac_f32_e32 v13, v99, v144
	v_fmac_f32_e32 v38, v100, v144
	v_fmac_f32_e32 v37, v101, v144
	v_fmac_f32_e32 v40, v102, v144
	v_fmac_f32_e32 v39, v103, v144
	v_fmac_f32_e32 v41, v104, v144
	v_fmac_f32_e32 v42, v105, v144
	v_fmac_f32_e32 v43, v106, v144
	v_fmac_f32_e32 v47, v108, v144
	v_fmac_f32_e32 v107, v111, v144
	v_fmac_f32_e32 v109, v114, v144
	v_fmac_f32_e32 v110, v117, v144
	v_fmac_f32_e32 v112, v120, v144
	v_fmac_f32_e32 v113, v123, v144
	v_fmac_f32_e32 v115, v126, v144
	v_fmac_f32_e32 v116, v127, v144
	v_fmac_f32_e32 v118, v136, v144
	v_fmac_f32_e32 v119, v137, v144
	v_fmac_f32_e32 v121, v138, v144
	v_fmac_f32_e32 v122, v139, v144
	v_fmac_f32_e32 v124, v140, v144
	v_fmac_f32_e32 v125, v141, v144
	v_fmac_f32_e32 v128, v142, v144
	v_fma_f32 v129, v143, v144, v91
	v_fmac_f32_e32 v36, v97, v145
	v_fmac_f32_e32 v13, v98, v145
	v_fmac_f32_e32 v38, v99, v145
	v_fmac_f32_e32 v37, v100, v145
	v_fmac_f32_e32 v40, v101, v145
	v_fmac_f32_e32 v39, v102, v145
	v_fmac_f32_e32 v41, v103, v145
	v_fmac_f32_e32 v42, v104, v145
	v_fmac_f32_e32 v43, v105, v145
	v_fmac_f32_e32 v47, v106, v145
	v_fmac_f32_e32 v107, v108, v145
	v_fmac_f32_e32 v109, v111, v145
	v_fmac_f32_e32 v110, v114, v145
	v_fmac_f32_e32 v112, v117, v145
	v_fmac_f32_e32 v113, v120, v145
	v_fmac_f32_e32 v115, v123, v145
	v_fmac_f32_e32 v116, v126, v145
	v_fmac_f32_e32 v118, v127, v145
	v_fmac_f32_e32 v119, v136, v145
	v_fmac_f32_e32 v121, v137, v145
	v_fmac_f32_e32 v122, v138, v145
	v_fmac_f32_e32 v124, v139, v145
	v_fmac_f32_e32 v125, v140, v145
	v_fmac_f32_e32 v128, v141, v145
	v_fmac_f32_e32 v129, v142, v145
	v_fma_f32 v130, v143, v145, v91
	ds_read2st64_b32 v[144:145], v52 offset0:224 offset1:232
	s_waitcnt lgkmcnt(1)
	v_fmac_f32_e32 v36, v96, v14
	v_fmac_f32_e32 v13, v97, v14
	v_fmac_f32_e32 v38, v98, v14
	v_fmac_f32_e32 v37, v99, v14
	v_fmac_f32_e32 v40, v100, v14
	v_fmac_f32_e32 v39, v101, v14
	v_fmac_f32_e32 v41, v102, v14
	v_fmac_f32_e32 v42, v103, v14
	v_fmac_f32_e32 v43, v104, v14
	v_fmac_f32_e32 v47, v105, v14
	v_fmac_f32_e32 v107, v106, v14
	v_fmac_f32_e32 v109, v108, v14
	v_fmac_f32_e32 v110, v111, v14
	v_fmac_f32_e32 v112, v114, v14
	v_fmac_f32_e32 v113, v117, v14
	v_fmac_f32_e32 v115, v120, v14
	v_fmac_f32_e32 v116, v123, v14
	v_fmac_f32_e32 v118, v126, v14
	v_fmac_f32_e32 v119, v127, v14
	v_fmac_f32_e32 v121, v136, v14
	v_fmac_f32_e32 v122, v137, v14
	v_fmac_f32_e32 v124, v138, v14
	v_fmac_f32_e32 v125, v139, v14
	v_fmac_f32_e32 v128, v140, v14
	v_fmac_f32_e32 v129, v141, v14
	v_fmac_f32_e32 v130, v142, v14
	v_fma_f32 v131, v143, v14, v91
	v_fmac_f32_e32 v36, v95, v15
	v_fmac_f32_e32 v13, v96, v15
	v_fmac_f32_e32 v38, v97, v15
	v_fmac_f32_e32 v37, v98, v15
	v_fmac_f32_e32 v40, v99, v15
	v_fmac_f32_e32 v39, v100, v15
	v_fmac_f32_e32 v41, v101, v15
	v_fmac_f32_e32 v42, v102, v15
	v_fmac_f32_e32 v43, v103, v15
	v_fmac_f32_e32 v47, v104, v15
	v_fmac_f32_e32 v107, v105, v15
	v_fmac_f32_e32 v109, v106, v15
	v_fmac_f32_e32 v110, v108, v15
	v_fmac_f32_e32 v112, v111, v15
	v_fmac_f32_e32 v113, v114, v15
	v_fmac_f32_e32 v115, v117, v15
	v_fmac_f32_e32 v116, v120, v15
	v_fmac_f32_e32 v118, v123, v15
	v_fmac_f32_e32 v119, v126, v15
	v_fmac_f32_e32 v121, v127, v15
	v_fmac_f32_e32 v122, v136, v15
	v_fmac_f32_e32 v124, v137, v15
	v_fmac_f32_e32 v125, v138, v15
	v_fmac_f32_e32 v128, v139, v15
	v_fmac_f32_e32 v129, v140, v15
	v_fmac_f32_e32 v130, v141, v15
	v_fmac_f32_e32 v131, v142, v15
	v_fma_f32 v132, v143, v15, v91
	ds_read2st64_b32 v[14:15], v52 offset0:240 offset1:248
	s_waitcnt lgkmcnt(1)
	v_fmac_f32_e32 v36, v94, v144
	v_fmac_f32_e32 v13, v95, v144
	v_fmac_f32_e32 v38, v96, v144
	v_fmac_f32_e32 v37, v97, v144
	v_fmac_f32_e32 v40, v98, v144
	v_fmac_f32_e32 v39, v99, v144
	v_fmac_f32_e32 v41, v100, v144
	v_fmac_f32_e32 v42, v101, v144
	v_fmac_f32_e32 v43, v102, v144
	v_fmac_f32_e32 v47, v103, v144
	v_fmac_f32_e32 v107, v104, v144
	v_fmac_f32_e32 v109, v105, v144
	v_fmac_f32_e32 v110, v106, v144
	v_fmac_f32_e32 v112, v108, v144
	v_fmac_f32_e32 v113, v111, v144
	v_fmac_f32_e32 v115, v114, v144
	v_fmac_f32_e32 v116, v117, v144
	v_fmac_f32_e32 v118, v120, v144
	v_fmac_f32_e32 v119, v123, v144
	v_fmac_f32_e32 v121, v126, v144
	v_fmac_f32_e32 v122, v127, v144
	v_fmac_f32_e32 v124, v136, v144
	v_fmac_f32_e32 v125, v137, v144
	v_fmac_f32_e32 v128, v138, v144
	v_fmac_f32_e32 v129, v139, v144
	v_fmac_f32_e32 v130, v140, v144
	v_fmac_f32_e32 v131, v141, v144
	v_fmac_f32_e32 v132, v142, v144
	v_fma_f32 v133, v143, v144, v91
	v_fmac_f32_e32 v36, v93, v145
	v_fmac_f32_e32 v13, v94, v145
	v_fmac_f32_e32 v38, v95, v145
	v_fmac_f32_e32 v37, v96, v145
	v_fmac_f32_e32 v40, v97, v145
	v_fmac_f32_e32 v39, v98, v145
	v_fmac_f32_e32 v41, v99, v145
	v_fmac_f32_e32 v42, v100, v145
	v_fmac_f32_e32 v43, v101, v145
	v_fmac_f32_e32 v47, v102, v145
	v_fmac_f32_e32 v107, v103, v145
	v_fmac_f32_e32 v109, v104, v145
	v_fmac_f32_e32 v110, v105, v145
	v_fmac_f32_e32 v112, v106, v145
	v_fmac_f32_e32 v113, v108, v145
	v_fmac_f32_e32 v115, v111, v145
	v_fmac_f32_e32 v116, v114, v145
	v_fmac_f32_e32 v118, v117, v145
	v_fmac_f32_e32 v119, v120, v145
	v_fmac_f32_e32 v121, v123, v145
	v_fmac_f32_e32 v122, v126, v145
	v_fmac_f32_e32 v124, v127, v145
	v_fmac_f32_e32 v125, v136, v145
	v_fmac_f32_e32 v128, v137, v145
	v_fmac_f32_e32 v129, v138, v145
	v_fmac_f32_e32 v130, v139, v145
	v_fmac_f32_e32 v131, v140, v145
	v_fmac_f32_e32 v132, v141, v145
	v_fmac_f32_e32 v133, v142, v145
	v_fma_f32 v134, v143, v145, v91
	ds_read_b32 v144, v53
	s_waitcnt lgkmcnt(1)
; #define LAS __attribute__((address_space(3)))
;     static __device__ __forceinline__ void run(float (&acc)[32], const float (&w)[31], const LAS float* us) {
;         const float v = us[J * 512];
;         constexpr int TLO = (J - 30 > 0) ? J - 30 : 0, THI = (J < 31) ? J : 31;
; #pragma unroll
;         for (int t = TLO; t <= THI; ++t) acc[t] += v * w[J - t];
;         if constexpr (J + 1 < 62) CfLds<J + 1>::run(acc, w, us);
;     }
	v_fmac_f32_e32 v36, v92, v14
	v_fmac_f32_e32 v13, v93, v14
	v_fmac_f32_e32 v38, v94, v14
	v_fmac_f32_e32 v37, v95, v14
	v_fmac_f32_e32 v40, v96, v14
	v_fmac_f32_e32 v39, v97, v14
	v_fmac_f32_e32 v41, v98, v14
	v_fmac_f32_e32 v42, v99, v14
	v_fmac_f32_e32 v43, v100, v14
	v_fmac_f32_e32 v47, v101, v14
	v_fmac_f32_e32 v107, v102, v14
	v_fmac_f32_e32 v109, v103, v14
	v_fmac_f32_e32 v110, v104, v14
	v_fmac_f32_e32 v112, v105, v14
	v_fmac_f32_e32 v113, v106, v14
	v_fmac_f32_e32 v115, v108, v14
	v_fmac_f32_e32 v116, v111, v14
	v_fmac_f32_e32 v118, v114, v14
	v_fmac_f32_e32 v119, v117, v14
	v_fmac_f32_e32 v121, v120, v14
	v_fmac_f32_e32 v122, v123, v14
	v_fmac_f32_e32 v124, v126, v14
	v_fmac_f32_e32 v125, v127, v14
	v_fmac_f32_e32 v128, v136, v14
	v_fmac_f32_e32 v129, v137, v14
	v_fmac_f32_e32 v130, v138, v14
	v_fmac_f32_e32 v131, v139, v14
	v_fmac_f32_e32 v132, v140, v14
	v_fmac_f32_e32 v133, v141, v14
	v_fmac_f32_e32 v134, v142, v14
	v_fma_f32 v135, v143, v14, v91
	v_fmac_f32_e32 v38, v93, v15
	v_fmac_f32_e32 v37, v94, v15
	v_fmac_f32_e32 v40, v95, v15
	v_fmac_f32_e32 v39, v96, v15
	v_fmac_f32_e32 v41, v97, v15
	v_fmac_f32_e32 v42, v98, v15
	v_fmac_f32_e32 v43, v99, v15
	v_fmac_f32_e32 v47, v100, v15
	v_fmac_f32_e32 v107, v101, v15
	v_fmac_f32_e32 v109, v102, v15
	v_fmac_f32_e32 v110, v103, v15
	v_fmac_f32_e32 v112, v104, v15
	v_fmac_f32_e32 v113, v105, v15
	v_fmac_f32_e32 v115, v106, v15
	v_fmac_f32_e32 v116, v108, v15
	v_fmac_f32_e32 v118, v111, v15
	v_fmac_f32_e32 v119, v114, v15
	v_fmac_f32_e32 v121, v117, v15
	v_fmac_f32_e32 v122, v120, v15
	v_fmac_f32_e32 v124, v123, v15
	v_fmac_f32_e32 v125, v126, v15
	v_fmac_f32_e32 v128, v127, v15
	v_fmac_f32_e32 v129, v136, v15
	v_fmac_f32_e32 v130, v137, v15
	v_fmac_f32_e32 v131, v138, v15
	v_fmac_f32_e32 v132, v139, v15
	v_fmac_f32_e32 v133, v140, v15
	v_fmac_f32_e32 v134, v141, v15
	v_fmac_f32_e32 v135, v142, v15
	v_fmac_f32_e32 v91, v143, v15
	ds_read_b32 v14, v54
	s_waitcnt lgkmcnt(1)
	v_fmac_f32_e32 v38, v92, v144
	v_fmac_f32_e32 v37, v93, v144
	v_fmac_f32_e32 v40, v94, v144
	v_fmac_f32_e32 v39, v95, v144
	v_fmac_f32_e32 v41, v96, v144
	v_fmac_f32_e32 v42, v97, v144
	v_fmac_f32_e32 v43, v98, v144
	v_fmac_f32_e32 v47, v99, v144
	v_fmac_f32_e32 v107, v100, v144
	v_fmac_f32_e32 v109, v101, v144
	v_fmac_f32_e32 v110, v102, v144
	v_fmac_f32_e32 v112, v103, v144
	v_fmac_f32_e32 v113, v104, v144
	v_fmac_f32_e32 v115, v105, v144
	v_fmac_f32_e32 v116, v106, v144
	v_fmac_f32_e32 v118, v108, v144
	v_fmac_f32_e32 v119, v111, v144
	v_fmac_f32_e32 v121, v114, v144
	v_fmac_f32_e32 v122, v117, v144
	v_fmac_f32_e32 v124, v120, v144
	v_fmac_f32_e32 v125, v123, v144
	v_fmac_f32_e32 v128, v126, v144
	v_fmac_f32_e32 v129, v127, v144
	v_fmac_f32_e32 v130, v136, v144
	v_fmac_f32_e32 v131, v137, v144
	v_fmac_f32_e32 v132, v138, v144
	v_fmac_f32_e32 v133, v139, v144
	v_fmac_f32_e32 v134, v140, v144
	v_fmac_f32_e32 v135, v141, v144
	v_fmac_f32_e32 v91, v142, v144
	v_fmac_f32_e32 v13, v92, v15
	ds_read_b32 v144, v55
	s_waitcnt lgkmcnt(1)
	v_fmac_f32_e32 v37, v92, v14
	v_fmac_f32_e32 v40, v93, v14
	v_fmac_f32_e32 v39, v94, v14
	v_fmac_f32_e32 v41, v95, v14
	v_fmac_f32_e32 v42, v96, v14
	v_fmac_f32_e32 v43, v97, v14
	v_fmac_f32_e32 v47, v98, v14
	v_fmac_f32_e32 v107, v99, v14
	v_fmac_f32_e32 v109, v100, v14
	v_fmac_f32_e32 v110, v101, v14
	v_fmac_f32_e32 v112, v102, v14
	v_fmac_f32_e32 v113, v103, v14
	v_fmac_f32_e32 v115, v104, v14
	v_fmac_f32_e32 v116, v105, v14
	v_fmac_f32_e32 v118, v106, v14
	v_fmac_f32_e32 v119, v108, v14
	v_fmac_f32_e32 v121, v111, v14
	v_fmac_f32_e32 v122, v114, v14
	v_fmac_f32_e32 v124, v117, v14
	v_fmac_f32_e32 v125, v120, v14
	v_fmac_f32_e32 v128, v123, v14
	v_fmac_f32_e32 v129, v126, v14
	v_fmac_f32_e32 v130, v127, v14
	v_fmac_f32_e32 v131, v136, v14
	v_fmac_f32_e32 v132, v137, v14
	v_fmac_f32_e32 v133, v138, v14
	v_fmac_f32_e32 v134, v139, v14
	v_fmac_f32_e32 v135, v140, v14
	v_fmac_f32_e32 v91, v141, v14
	ds_read_b32 v14, v56
	s_waitcnt lgkmcnt(1)
	v_fmac_f32_e32 v40, v92, v144
	v_fmac_f32_e32 v39, v93, v144
	v_fmac_f32_e32 v41, v94, v144
	v_fmac_f32_e32 v42, v95, v144
	v_fmac_f32_e32 v43, v96, v144
	v_fmac_f32_e32 v47, v97, v144
	v_fmac_f32_e32 v107, v98, v144
	v_fmac_f32_e32 v109, v99, v144
	v_fmac_f32_e32 v110, v100, v144
	v_fmac_f32_e32 v112, v101, v144
	v_fmac_f32_e32 v113, v102, v144
	v_fmac_f32_e32 v115, v103, v144
	v_fmac_f32_e32 v116, v104, v144
	v_fmac_f32_e32 v118, v105, v144
	v_fmac_f32_e32 v119, v106, v144
	v_fmac_f32_e32 v121, v108, v144
	v_fmac_f32_e32 v122, v111, v144
	v_fmac_f32_e32 v124, v114, v144
	v_fmac_f32_e32 v125, v117, v144
	v_fmac_f32_e32 v128, v120, v144
	v_fmac_f32_e32 v129, v123, v144
	v_fmac_f32_e32 v130, v126, v144
	v_fmac_f32_e32 v131, v127, v144
	v_fmac_f32_e32 v132, v136, v144
	v_fmac_f32_e32 v133, v137, v144
	v_fmac_f32_e32 v134, v138, v144
	v_fmac_f32_e32 v135, v139, v144
	v_fmac_f32_e32 v91, v140, v144
	ds_read_b32 v144, v57
	s_waitcnt lgkmcnt(1)
	v_fmac_f32_e32 v39, v92, v14
	v_fmac_f32_e32 v41, v93, v14
	v_fmac_f32_e32 v42, v94, v14
	v_fmac_f32_e32 v43, v95, v14
	v_fmac_f32_e32 v47, v96, v14
	v_fmac_f32_e32 v107, v97, v14
	v_fmac_f32_e32 v109, v98, v14
	v_fmac_f32_e32 v110, v99, v14
	v_fmac_f32_e32 v112, v100, v14
	v_fmac_f32_e32 v113, v101, v14
	v_fmac_f32_e32 v115, v102, v14
	v_fmac_f32_e32 v116, v103, v14
	v_fmac_f32_e32 v118, v104, v14
	v_fmac_f32_e32 v119, v105, v14
	v_fmac_f32_e32 v121, v106, v14
	v_fmac_f32_e32 v122, v108, v14
	v_fmac_f32_e32 v124, v111, v14
	v_fmac_f32_e32 v125, v114, v14
	v_fmac_f32_e32 v128, v117, v14
	v_fmac_f32_e32 v129, v120, v14
	v_fmac_f32_e32 v130, v123, v14
	v_fmac_f32_e32 v131, v126, v14
	v_fmac_f32_e32 v132, v127, v14
	v_fmac_f32_e32 v133, v136, v14
	v_fmac_f32_e32 v134, v137, v14
	v_fmac_f32_e32 v135, v138, v14
	v_fmac_f32_e32 v91, v139, v14
	ds_read_b32 v14, v58
	s_waitcnt lgkmcnt(1)
; #define LAS __attribute__((address_space(3)))
;     static __device__ __forceinline__ void run(float (&acc)[32], const float (&w)[31], const LAS float* us) {
;         const float v = us[J * 512];
;         constexpr int TLO = (J - 30 > 0) ? J - 30 : 0, THI = (J < 31) ? J : 31;
; #pragma unroll
;         for (int t = TLO; t <= THI; ++t) acc[t] += v * w[J - t];
;         if constexpr (J + 1 < 62) CfLds<J + 1>::run(acc, w, us);
;     }
	v_fmac_f32_e32 v41, v92, v144
	v_fmac_f32_e32 v42, v93, v144
	v_fmac_f32_e32 v43, v94, v144
	v_fmac_f32_e32 v47, v95, v144
	v_fmac_f32_e32 v107, v96, v144
	v_fmac_f32_e32 v109, v97, v144
	v_fmac_f32_e32 v110, v98, v144
	v_fmac_f32_e32 v112, v99, v144
	v_fmac_f32_e32 v113, v100, v144
	v_fmac_f32_e32 v115, v101, v144
	v_fmac_f32_e32 v116, v102, v144
	v_fmac_f32_e32 v118, v103, v144
	v_fmac_f32_e32 v119, v104, v144
	v_fmac_f32_e32 v121, v105, v144
	v_fmac_f32_e32 v122, v106, v144
	v_fmac_f32_e32 v124, v108, v144
	v_fmac_f32_e32 v125, v111, v144
	v_fmac_f32_e32 v128, v114, v144
	v_fmac_f32_e32 v129, v117, v144
	v_fmac_f32_e32 v130, v120, v144
	v_fmac_f32_e32 v131, v123, v144
	v_fmac_f32_e32 v132, v126, v144
	v_fmac_f32_e32 v133, v127, v144
	v_fmac_f32_e32 v134, v136, v144
	v_fmac_f32_e32 v135, v137, v144
	v_fmac_f32_e32 v91, v138, v144
	ds_read_b32 v144, v59
	s_waitcnt lgkmcnt(1)
	v_fmac_f32_e32 v42, v92, v14
	v_fmac_f32_e32 v43, v93, v14
	v_fmac_f32_e32 v47, v94, v14
	v_fmac_f32_e32 v107, v95, v14
	v_fmac_f32_e32 v109, v96, v14
	v_fmac_f32_e32 v110, v97, v14
	v_fmac_f32_e32 v112, v98, v14
	v_fmac_f32_e32 v113, v99, v14
	v_fmac_f32_e32 v115, v100, v14
	v_fmac_f32_e32 v116, v101, v14
	v_fmac_f32_e32 v118, v102, v14
	v_fmac_f32_e32 v119, v103, v14
	v_fmac_f32_e32 v121, v104, v14
	v_fmac_f32_e32 v122, v105, v14
	v_fmac_f32_e32 v124, v106, v14
	v_fmac_f32_e32 v125, v108, v14
	v_fmac_f32_e32 v128, v111, v14
	v_fmac_f32_e32 v129, v114, v14
	v_fmac_f32_e32 v130, v117, v14
	v_fmac_f32_e32 v131, v120, v14
	v_fmac_f32_e32 v132, v123, v14
	v_fmac_f32_e32 v133, v126, v14
	v_fmac_f32_e32 v134, v127, v14
	v_fmac_f32_e32 v135, v136, v14
	v_fmac_f32_e32 v91, v137, v14
	ds_read_b32 v14, v60
	s_waitcnt lgkmcnt(1)
	v_fmac_f32_e32 v43, v92, v144
	v_fmac_f32_e32 v47, v93, v144
	v_fmac_f32_e32 v107, v94, v144
	v_fmac_f32_e32 v109, v95, v144
	v_fmac_f32_e32 v110, v96, v144
	v_fmac_f32_e32 v112, v97, v144
	v_fmac_f32_e32 v113, v98, v144
	v_fmac_f32_e32 v115, v99, v144
	v_fmac_f32_e32 v116, v100, v144
	v_fmac_f32_e32 v118, v101, v144
	v_fmac_f32_e32 v119, v102, v144
	v_fmac_f32_e32 v121, v103, v144
	v_fmac_f32_e32 v122, v104, v144
	v_fmac_f32_e32 v124, v105, v144
	v_fmac_f32_e32 v125, v106, v144
	v_fmac_f32_e32 v128, v108, v144
	v_fmac_f32_e32 v129, v111, v144
	v_fmac_f32_e32 v130, v114, v144
	v_fmac_f32_e32 v131, v117, v144
	v_fmac_f32_e32 v132, v120, v144
	v_fmac_f32_e32 v133, v123, v144
	v_fmac_f32_e32 v134, v126, v144
	v_fmac_f32_e32 v135, v127, v144
	v_fmac_f32_e32 v91, v136, v144
	ds_read_b32 v144, v61
	s_waitcnt lgkmcnt(1)
	v_fmac_f32_e32 v47, v92, v14
	v_fmac_f32_e32 v107, v93, v14
	v_fmac_f32_e32 v109, v94, v14
	v_fmac_f32_e32 v110, v95, v14
	v_fmac_f32_e32 v112, v96, v14
	v_fmac_f32_e32 v113, v97, v14
	v_fmac_f32_e32 v115, v98, v14
	v_fmac_f32_e32 v116, v99, v14
	v_fmac_f32_e32 v118, v100, v14
	v_fmac_f32_e32 v119, v101, v14
	v_fmac_f32_e32 v121, v102, v14
	v_fmac_f32_e32 v122, v103, v14
	v_fmac_f32_e32 v124, v104, v14
	v_fmac_f32_e32 v125, v105, v14
	v_fmac_f32_e32 v128, v106, v14
	v_fmac_f32_e32 v129, v108, v14
	v_fmac_f32_e32 v130, v111, v14
	v_fmac_f32_e32 v131, v114, v14
	v_fmac_f32_e32 v132, v117, v14
	v_fmac_f32_e32 v133, v120, v14
	v_fmac_f32_e32 v134, v123, v14
	v_fmac_f32_e32 v135, v126, v14
	v_fmac_f32_e32 v91, v127, v14
	ds_read_b32 v14, v62
	s_waitcnt lgkmcnt(1)
	v_fmac_f32_e32 v107, v92, v144
	v_fmac_f32_e32 v109, v93, v144
	v_fmac_f32_e32 v110, v94, v144
	v_fmac_f32_e32 v112, v95, v144
	v_fmac_f32_e32 v113, v96, v144
	v_fmac_f32_e32 v115, v97, v144
	v_fmac_f32_e32 v116, v98, v144
	v_fmac_f32_e32 v118, v99, v144
	v_fmac_f32_e32 v119, v100, v144
	v_fmac_f32_e32 v121, v101, v144
	v_fmac_f32_e32 v122, v102, v144
	v_fmac_f32_e32 v124, v103, v144
	v_fmac_f32_e32 v125, v104, v144
	v_fmac_f32_e32 v128, v105, v144
	v_fmac_f32_e32 v129, v106, v144
	v_fmac_f32_e32 v130, v108, v144
	v_fmac_f32_e32 v131, v111, v144
	v_fmac_f32_e32 v132, v114, v144
	v_fmac_f32_e32 v133, v117, v144
	v_fmac_f32_e32 v134, v120, v144
	v_fmac_f32_e32 v135, v123, v144
	v_fmac_f32_e32 v91, v126, v144
	ds_read_b32 v144, v63
	s_waitcnt lgkmcnt(1)
	v_fmac_f32_e32 v109, v92, v14
	v_fmac_f32_e32 v110, v93, v14
	v_fmac_f32_e32 v112, v94, v14
	v_fmac_f32_e32 v113, v95, v14
	v_fmac_f32_e32 v115, v96, v14
	v_fmac_f32_e32 v116, v97, v14
	v_fmac_f32_e32 v118, v98, v14
	v_fmac_f32_e32 v119, v99, v14
	v_fmac_f32_e32 v121, v100, v14
	v_fmac_f32_e32 v122, v101, v14
	v_fmac_f32_e32 v124, v102, v14
	v_fmac_f32_e32 v125, v103, v14
	v_fmac_f32_e32 v128, v104, v14
	v_fmac_f32_e32 v129, v105, v14
	v_fmac_f32_e32 v130, v106, v14
	v_fmac_f32_e32 v131, v108, v14
	v_fmac_f32_e32 v132, v111, v14
	v_fmac_f32_e32 v133, v114, v14
	v_fmac_f32_e32 v134, v117, v14
	v_fmac_f32_e32 v135, v120, v14
	v_fmac_f32_e32 v91, v123, v14
	ds_read_b32 v14, v64
	s_waitcnt lgkmcnt(1)
	v_fmac_f32_e32 v110, v92, v144
	v_fmac_f32_e32 v112, v93, v144
	v_fmac_f32_e32 v113, v94, v144
	v_fmac_f32_e32 v115, v95, v144
	v_fmac_f32_e32 v116, v96, v144
	v_fmac_f32_e32 v118, v97, v144
	v_fmac_f32_e32 v119, v98, v144
	v_fmac_f32_e32 v121, v99, v144
	v_fmac_f32_e32 v122, v100, v144
	v_fmac_f32_e32 v124, v101, v144
	v_fmac_f32_e32 v125, v102, v144
	v_fmac_f32_e32 v128, v103, v144
	v_fmac_f32_e32 v129, v104, v144
	v_fmac_f32_e32 v130, v105, v144
	v_fmac_f32_e32 v131, v106, v144
	v_fmac_f32_e32 v132, v108, v144
	v_fmac_f32_e32 v133, v111, v144
	v_fmac_f32_e32 v134, v114, v144
	v_fmac_f32_e32 v135, v117, v144
	v_fmac_f32_e32 v91, v120, v144
	ds_read_b32 v144, v65
	s_waitcnt lgkmcnt(1)
; #define LAS __attribute__((address_space(3)))
;     static __device__ __forceinline__ void run(float (&acc)[32], const float (&w)[31], const LAS float* us) {
;         const float v = us[J * 512];
;         constexpr int TLO = (J - 30 > 0) ? J - 30 : 0, THI = (J < 31) ? J : 31;
; #pragma unroll
;         for (int t = TLO; t <= THI; ++t) acc[t] += v * w[J - t];
;         if constexpr (J + 1 < 62) CfLds<J + 1>::run(acc, w, us);
;     }
	v_fmac_f32_e32 v112, v92, v14
	v_fmac_f32_e32 v113, v93, v14
	v_fmac_f32_e32 v115, v94, v14
	v_fmac_f32_e32 v116, v95, v14
	v_fmac_f32_e32 v118, v96, v14
	v_fmac_f32_e32 v119, v97, v14
	v_fmac_f32_e32 v121, v98, v14
	v_fmac_f32_e32 v122, v99, v14
	v_fmac_f32_e32 v124, v100, v14
	v_fmac_f32_e32 v125, v101, v14
	v_fmac_f32_e32 v128, v102, v14
	v_fmac_f32_e32 v129, v103, v14
	v_fmac_f32_e32 v130, v104, v14
	v_fmac_f32_e32 v131, v105, v14
	v_fmac_f32_e32 v132, v106, v14
	v_fmac_f32_e32 v133, v108, v14
	v_fmac_f32_e32 v134, v111, v14
	v_fmac_f32_e32 v135, v114, v14
	v_fmac_f32_e32 v91, v117, v14
	ds_read_b32 v14, v66
	s_waitcnt lgkmcnt(1)
	v_fmac_f32_e32 v113, v92, v144
	v_fmac_f32_e32 v115, v93, v144
	v_fmac_f32_e32 v116, v94, v144
	v_fmac_f32_e32 v118, v95, v144
	v_fmac_f32_e32 v119, v96, v144
	v_fmac_f32_e32 v121, v97, v144
	v_fmac_f32_e32 v122, v98, v144
	v_fmac_f32_e32 v124, v99, v144
	v_fmac_f32_e32 v125, v100, v144
	v_fmac_f32_e32 v128, v101, v144
	v_fmac_f32_e32 v129, v102, v144
	v_fmac_f32_e32 v130, v103, v144
	v_fmac_f32_e32 v131, v104, v144
	v_fmac_f32_e32 v132, v105, v144
	v_fmac_f32_e32 v133, v106, v144
	v_fmac_f32_e32 v134, v108, v144
	v_fmac_f32_e32 v135, v111, v144
	v_fmac_f32_e32 v91, v114, v144
	ds_read_b32 v144, v67
	s_waitcnt lgkmcnt(1)
	v_fmac_f32_e32 v115, v92, v14
	v_fmac_f32_e32 v116, v93, v14
	v_fmac_f32_e32 v118, v94, v14
	v_fmac_f32_e32 v119, v95, v14
	v_fmac_f32_e32 v121, v96, v14
	v_fmac_f32_e32 v122, v97, v14
	v_fmac_f32_e32 v124, v98, v14
	v_fmac_f32_e32 v125, v99, v14
	v_fmac_f32_e32 v128, v100, v14
	v_fmac_f32_e32 v129, v101, v14
	v_fmac_f32_e32 v130, v102, v14
	v_fmac_f32_e32 v131, v103, v14
	v_fmac_f32_e32 v132, v104, v14
	v_fmac_f32_e32 v133, v105, v14
	v_fmac_f32_e32 v134, v106, v14
	v_fmac_f32_e32 v135, v108, v14
	v_fmac_f32_e32 v91, v111, v14
	ds_read_b32 v14, v68
	s_waitcnt lgkmcnt(1)
	v_fmac_f32_e32 v116, v92, v144
	v_fmac_f32_e32 v118, v93, v144
	v_fmac_f32_e32 v119, v94, v144
	v_fmac_f32_e32 v121, v95, v144
	v_fmac_f32_e32 v122, v96, v144
	v_fmac_f32_e32 v124, v97, v144
	v_fmac_f32_e32 v125, v98, v144
	v_fmac_f32_e32 v128, v99, v144
	v_fmac_f32_e32 v129, v100, v144
	v_fmac_f32_e32 v130, v101, v144
	v_fmac_f32_e32 v131, v102, v144
	v_fmac_f32_e32 v132, v103, v144
	v_fmac_f32_e32 v133, v104, v144
	v_fmac_f32_e32 v134, v105, v144
	v_fmac_f32_e32 v135, v106, v144
	v_fmac_f32_e32 v91, v108, v144
	ds_read_b32 v144, v69
	s_waitcnt lgkmcnt(1)
	v_fmac_f32_e32 v118, v92, v14
	v_fmac_f32_e32 v119, v93, v14
	v_fmac_f32_e32 v121, v94, v14
	v_fmac_f32_e32 v122, v95, v14
	v_fmac_f32_e32 v124, v96, v14
	v_fmac_f32_e32 v125, v97, v14
	v_fmac_f32_e32 v128, v98, v14
	v_fmac_f32_e32 v129, v99, v14
	v_fmac_f32_e32 v130, v100, v14
	v_fmac_f32_e32 v131, v101, v14
	v_fmac_f32_e32 v132, v102, v14
	v_fmac_f32_e32 v133, v103, v14
	v_fmac_f32_e32 v134, v104, v14
	v_fmac_f32_e32 v135, v105, v14
	v_fmac_f32_e32 v91, v106, v14
	ds_read_b32 v14, v70
	s_waitcnt lgkmcnt(1)
	v_fmac_f32_e32 v119, v92, v144
	v_fmac_f32_e32 v121, v93, v144
	v_fmac_f32_e32 v122, v94, v144
	v_fmac_f32_e32 v124, v95, v144
	v_fmac_f32_e32 v125, v96, v144
	v_fmac_f32_e32 v128, v97, v144
	v_fmac_f32_e32 v129, v98, v144
	v_fmac_f32_e32 v130, v99, v144
	v_fmac_f32_e32 v131, v100, v144
	v_fmac_f32_e32 v132, v101, v144
	v_fmac_f32_e32 v133, v102, v144
	v_fmac_f32_e32 v134, v103, v144
	v_fmac_f32_e32 v135, v104, v144
	v_fmac_f32_e32 v91, v105, v144
	ds_read_b32 v144, v71
	s_waitcnt lgkmcnt(1)
	v_fmac_f32_e32 v121, v92, v14
	v_fmac_f32_e32 v122, v93, v14
	v_fmac_f32_e32 v124, v94, v14
	v_fmac_f32_e32 v125, v95, v14
	v_fmac_f32_e32 v128, v96, v14
	v_fmac_f32_e32 v129, v97, v14
	v_fmac_f32_e32 v130, v98, v14
	v_fmac_f32_e32 v131, v99, v14
	v_fmac_f32_e32 v132, v100, v14
	v_fmac_f32_e32 v133, v101, v14
	v_fmac_f32_e32 v134, v102, v14
	v_fmac_f32_e32 v135, v103, v14
	v_fmac_f32_e32 v91, v104, v14
	ds_read_b32 v14, v72
	s_waitcnt lgkmcnt(1)
	v_fmac_f32_e32 v122, v92, v144
	v_fmac_f32_e32 v124, v93, v144
	v_fmac_f32_e32 v125, v94, v144
	v_fmac_f32_e32 v128, v95, v144
	v_fmac_f32_e32 v129, v96, v144
	v_fmac_f32_e32 v130, v97, v144
	v_fmac_f32_e32 v131, v98, v144
	v_fmac_f32_e32 v132, v99, v144
	v_fmac_f32_e32 v133, v100, v144
	v_fmac_f32_e32 v134, v101, v144
	v_fmac_f32_e32 v135, v102, v144
	v_fmac_f32_e32 v91, v103, v144
	ds_read_b32 v144, v73
	s_waitcnt lgkmcnt(1)
	v_fmac_f32_e32 v124, v92, v14
	v_fmac_f32_e32 v125, v93, v14
	v_fmac_f32_e32 v128, v94, v14
	v_fmac_f32_e32 v129, v95, v14
	v_fmac_f32_e32 v130, v96, v14
	v_fmac_f32_e32 v131, v97, v14
	v_fmac_f32_e32 v132, v98, v14
	v_fmac_f32_e32 v133, v99, v14
	v_fmac_f32_e32 v134, v100, v14
	v_fmac_f32_e32 v135, v101, v14
	v_fmac_f32_e32 v91, v102, v14
	ds_read_b32 v14, v74
	s_waitcnt lgkmcnt(1)
	v_fmac_f32_e32 v125, v92, v144
	v_fmac_f32_e32 v128, v93, v144
	v_fmac_f32_e32 v129, v94, v144
	v_fmac_f32_e32 v130, v95, v144
	v_fmac_f32_e32 v131, v96, v144
	v_fmac_f32_e32 v132, v97, v144
	v_fmac_f32_e32 v133, v98, v144
	v_fmac_f32_e32 v134, v99, v144
	v_fmac_f32_e32 v135, v100, v144
	v_fmac_f32_e32 v91, v101, v144
	ds_read_b32 v144, v75
	s_waitcnt lgkmcnt(1)
	v_fmac_f32_e32 v128, v92, v14
	v_fmac_f32_e32 v129, v93, v14
	v_fmac_f32_e32 v130, v94, v14
	v_fmac_f32_e32 v131, v95, v14
	v_fmac_f32_e32 v132, v96, v14
	v_fmac_f32_e32 v133, v97, v14
	v_fmac_f32_e32 v134, v98, v14
	v_fmac_f32_e32 v135, v99, v14
	v_fmac_f32_e32 v91, v100, v14
	ds_read_b32 v14, v76
	s_waitcnt lgkmcnt(1)
	v_fmac_f32_e32 v129, v92, v144
	v_fmac_f32_e32 v130, v93, v144
	v_fmac_f32_e32 v131, v94, v144
	v_fmac_f32_e32 v132, v95, v144
	v_fmac_f32_e32 v133, v96, v144
	v_fmac_f32_e32 v134, v97, v144
	v_fmac_f32_e32 v135, v98, v144
	v_fmac_f32_e32 v91, v99, v144
	ds_read_b32 v144, v77
	s_waitcnt lgkmcnt(1)
; #define LAS __attribute__((address_space(3)))
; __device__ __forceinline__ unsigned f2bf(float f) { unsigned u = __float_as_uint(f); return (u + 0x7fffu + ((u >> 16) & 1u)) >> 16; }
;     static __device__ __forceinline__ void run(float (&acc)[32], const float (&w)[31], const LAS float* us) {
;         const float v = us[J * 512];
;         constexpr int TLO = (J - 30 > 0) ? J - 30 : 0, THI = (J < 31) ? J : 31;
; #pragma unroll
;         for (int t = TLO; t <= THI; ++t) acc[t] += v * w[J - t];
;         if constexpr (J + 1 < 62) CfLds<J + 1>::run(acc, w, us);
;     }
; __device__ __forceinline__ void cf_prompt_items(LAS unsigned char* lds, const bf16_t* PROJ, int it0, int itstride, int nitems, const float* cw, const float* cb, bf16_t* CONVOUT, float* pcfc) {
;     ...
;         for (int t = 0; t < 32; ++t) CONVOUT[(size_t)(row0 + t) * DM + c0 + tid] = (bf16_t)f2bf(acc[t]);
	v_fmac_f32_e32 v130, v92, v14
	v_fmac_f32_e32 v131, v93, v14
	v_fmac_f32_e32 v132, v94, v14
	v_fmac_f32_e32 v133, v95, v14
	v_fmac_f32_e32 v134, v96, v14
	v_fmac_f32_e32 v135, v97, v14
	v_fmac_f32_e32 v91, v98, v14
	ds_read_b32 v14, v78
	s_waitcnt lgkmcnt(1)
	v_fmac_f32_e32 v131, v92, v144
	v_fmac_f32_e32 v132, v93, v144
	v_fmac_f32_e32 v133, v94, v144
	v_fmac_f32_e32 v134, v95, v144
	v_fmac_f32_e32 v135, v96, v144
	v_fmac_f32_e32 v91, v97, v144
	ds_read_b32 v144, v79
	s_waitcnt lgkmcnt(1)
	v_fmac_f32_e32 v132, v92, v14
	v_fmac_f32_e32 v133, v93, v14
	v_fmac_f32_e32 v134, v94, v14
	v_fmac_f32_e32 v135, v95, v14
	v_fmac_f32_e32 v91, v96, v14
	ds_read_b32 v14, v80
	s_waitcnt lgkmcnt(1)
	v_fmac_f32_e32 v133, v92, v144
	v_fmac_f32_e32 v134, v93, v144
	v_fmac_f32_e32 v135, v94, v144
	v_fmac_f32_e32 v91, v95, v144
	ds_read_b32 v144, v81
	s_waitcnt lgkmcnt(1)
	v_fmac_f32_e32 v134, v92, v14
	v_fmac_f32_e32 v135, v93, v14
	v_fmac_f32_e32 v91, v94, v14
	ds_read_b32 v14, v82
	s_waitcnt lgkmcnt(1)
	v_fmac_f32_e32 v135, v92, v144
	v_fmac_f32_e32 v91, v93, v144
	s_waitcnt lgkmcnt(0)
	v_fmac_f32_e32 v91, v92, v14
	v_lshl_add_u64 v[14:15], v[48:49], 0, s[38:39]
	v_bfe_u32 v92, v36, 16, 1
	v_add3_u32 v36, v36, v92, s90
	v_lshl_add_u64 v[92:93], v[14:15], 0, s[0:1]
	s_or_b32 s0, s82, 1
	s_ashr_i32 s1, s0, 31
	s_lshl_b64 s[0:1], s[0:1], 12
	global_store_short_d16_hi v[92:93], v36, off
	v_lshl_add_u64 v[92:93], v[14:15], 0, s[0:1]
	s_or_b32 s0, s82, 2
	v_bfe_u32 v36, v13, 16, 1
	s_ashr_i32 s1, s0, 31
	v_add3_u32 v13, v13, v36, s90
	s_lshl_b64 s[0:1], s[0:1], 12
	global_store_short_d16_hi v[92:93], v13, off
	v_bfe_u32 v13, v38, 16, 1
	v_lshl_add_u64 v[92:93], v[14:15], 0, s[0:1]
	s_or_b32 s0, s82, 3
	v_add3_u32 v13, v38, v13, s90
	s_ashr_i32 s1, s0, 31
	global_store_short_d16_hi v[92:93], v13, off
	v_bfe_u32 v13, v37, 16, 1
	s_lshl_b64 s[0:1], s[0:1], 12
	v_add3_u32 v13, v37, v13, s90
	v_lshl_add_u64 v[36:37], v[14:15], 0, s[0:1]
	s_or_b32 s0, s82, 4
	s_ashr_i32 s1, s0, 31
	s_lshl_b64 s[0:1], s[0:1], 12
	global_store_short_d16_hi v[36:37], v13, off
	v_lshl_add_u64 v[36:37], v[14:15], 0, s[0:1]
	s_or_b32 s0, s82, 5
	v_bfe_u32 v13, v40, 16, 1
	s_ashr_i32 s1, s0, 31
	v_add3_u32 v13, v40, v13, s90
	s_lshl_b64 s[0:1], s[0:1], 12
	global_store_short_d16_hi v[36:37], v13, off
	v_lshl_add_u64 v[36:37], v[14:15], 0, s[0:1]
	s_or_b32 s0, s82, 6
	v_bfe_u32 v13, v39, 16, 1
	s_ashr_i32 s1, s0, 31
	v_add3_u32 v13, v39, v13, s90
	s_lshl_b64 s[0:1], s[0:1], 12
	global_store_short_d16_hi v[36:37], v13, off
	v_lshl_add_u64 v[36:37], v[14:15], 0, s[0:1]
	s_or_b32 s0, s82, 7
	v_bfe_u32 v13, v41, 16, 1
	s_ashr_i32 s1, s0, 31
	v_add3_u32 v13, v41, v13, s90
	s_lshl_b64 s[0:1], s[0:1], 12
	global_store_short_d16_hi v[36:37], v13, off
	v_lshl_add_u64 v[36:37], v[14:15], 0, s[0:1]
	s_or_b32 s0, s82, 8
	v_bfe_u32 v13, v42, 16, 1
	s_ashr_i32 s1, s0, 31
	v_add3_u32 v13, v42, v13, s90
	s_lshl_b64 s[0:1], s[0:1], 12
	global_store_short_d16_hi v[36:37], v13, off
	v_lshl_add_u64 v[36:37], v[14:15], 0, s[0:1]
	s_or_b32 s0, s82, 9
	v_bfe_u32 v13, v43, 16, 1
	s_ashr_i32 s1, s0, 31
	v_add3_u32 v13, v43, v13, s90
	s_lshl_b64 s[0:1], s[0:1], 12
	global_store_short_d16_hi v[36:37], v13, off
	v_lshl_add_u64 v[36:37], v[14:15], 0, s[0:1]
	s_or_b32 s0, s82, 10
	v_bfe_u32 v13, v47, 16, 1
	s_ashr_i32 s1, s0, 31
	v_add3_u32 v13, v47, v13, s90
	s_lshl_b64 s[0:1], s[0:1], 12
	global_store_short_d16_hi v[36:37], v13, off
	v_lshl_add_u64 v[36:37], v[14:15], 0, s[0:1]
	s_or_b32 s0, s82, 11
	v_bfe_u32 v13, v107, 16, 1
	s_ashr_i32 s1, s0, 31
	v_add3_u32 v13, v107, v13, s90
	s_lshl_b64 s[0:1], s[0:1], 12
	global_store_short_d16_hi v[36:37], v13, off
	v_lshl_add_u64 v[36:37], v[14:15], 0, s[0:1]
	s_or_b32 s0, s82, 12
	v_bfe_u32 v13, v109, 16, 1
	s_ashr_i32 s1, s0, 31
	v_add3_u32 v13, v109, v13, s90
	s_lshl_b64 s[0:1], s[0:1], 12
	global_store_short_d16_hi v[36:37], v13, off
	v_lshl_add_u64 v[36:37], v[14:15], 0, s[0:1]
	s_or_b32 s0, s82, 13
	v_bfe_u32 v13, v110, 16, 1
	s_ashr_i32 s1, s0, 31
	v_add3_u32 v13, v110, v13, s90
	s_lshl_b64 s[0:1], s[0:1], 12
	global_store_short_d16_hi v[36:37], v13, off
	v_lshl_add_u64 v[36:37], v[14:15], 0, s[0:1]
	s_or_b32 s0, s82, 14
	v_bfe_u32 v13, v112, 16, 1
	s_ashr_i32 s1, s0, 31
; __device__ __forceinline__ unsigned f2bf(float f) { unsigned u = __float_as_uint(f); return (u + 0x7fffu + ((u >> 16) & 1u)) >> 16; }
; #define LDS_BARRIER() do { asm volatile("s_waitcnt lgkmcnt(0)" ::: "memory"); __builtin_amdgcn_s_barrier(); asm volatile("" ::: "memory"); } while (0)
; __device__ __forceinline__ void cf_prompt_items(LAS unsigned char* lds, const bf16_t* PROJ, int it0, int itstride, int nitems, const float* cw, const float* cb, bf16_t* CONVOUT, float* pcfc) {
;     ...
;         for (int t = 0; t < 32; ++t) CONVOUT[(size_t)(row0 + t) * DM + c0 + tid] = (bf16_t)f2bf(acc[t]);
;         LDS_BARRIER();
	v_add3_u32 v13, v112, v13, s90
	s_lshl_b64 s[0:1], s[0:1], 12
	global_store_short_d16_hi v[36:37], v13, off
	v_lshl_add_u64 v[36:37], v[14:15], 0, s[0:1]
	s_or_b32 s0, s82, 15
	v_bfe_u32 v13, v113, 16, 1
	s_ashr_i32 s1, s0, 31
	v_add3_u32 v13, v113, v13, s90
	s_lshl_b64 s[0:1], s[0:1], 12
	global_store_short_d16_hi v[36:37], v13, off
	v_lshl_add_u64 v[36:37], v[14:15], 0, s[0:1]
	s_or_b32 s0, s82, 16
	v_bfe_u32 v13, v115, 16, 1
	s_ashr_i32 s1, s0, 31
	v_add3_u32 v13, v115, v13, s90
	s_lshl_b64 s[0:1], s[0:1], 12
	global_store_short_d16_hi v[36:37], v13, off
	v_lshl_add_u64 v[36:37], v[14:15], 0, s[0:1]
	s_or_b32 s0, s82, 17
	v_bfe_u32 v13, v116, 16, 1
	s_ashr_i32 s1, s0, 31
	v_add3_u32 v13, v116, v13, s90
	s_lshl_b64 s[0:1], s[0:1], 12
	global_store_short_d16_hi v[36:37], v13, off
	v_lshl_add_u64 v[36:37], v[14:15], 0, s[0:1]
	s_or_b32 s0, s82, 18
	v_bfe_u32 v13, v118, 16, 1
	s_ashr_i32 s1, s0, 31
	v_add3_u32 v13, v118, v13, s90
	s_lshl_b64 s[0:1], s[0:1], 12
	global_store_short_d16_hi v[36:37], v13, off
	v_lshl_add_u64 v[36:37], v[14:15], 0, s[0:1]
	s_or_b32 s0, s82, 19
	v_bfe_u32 v13, v119, 16, 1
	s_ashr_i32 s1, s0, 31
	v_add3_u32 v13, v119, v13, s90
	s_lshl_b64 s[0:1], s[0:1], 12
	global_store_short_d16_hi v[36:37], v13, off
	v_lshl_add_u64 v[36:37], v[14:15], 0, s[0:1]
	s_or_b32 s0, s82, 20
	v_bfe_u32 v13, v121, 16, 1
	s_ashr_i32 s1, s0, 31
	v_add3_u32 v13, v121, v13, s90
	s_lshl_b64 s[0:1], s[0:1], 12
	global_store_short_d16_hi v[36:37], v13, off
	v_lshl_add_u64 v[36:37], v[14:15], 0, s[0:1]
	s_or_b32 s0, s82, 21
	v_bfe_u32 v13, v122, 16, 1
	s_ashr_i32 s1, s0, 31
	v_add3_u32 v13, v122, v13, s90
	s_lshl_b64 s[0:1], s[0:1], 12
	global_store_short_d16_hi v[36:37], v13, off
	v_lshl_add_u64 v[36:37], v[14:15], 0, s[0:1]
	s_or_b32 s0, s82, 22
	v_bfe_u32 v13, v124, 16, 1
	s_ashr_i32 s1, s0, 31
	v_add3_u32 v13, v124, v13, s90
	s_lshl_b64 s[0:1], s[0:1], 12
	global_store_short_d16_hi v[36:37], v13, off
	v_lshl_add_u64 v[36:37], v[14:15], 0, s[0:1]
	s_or_b32 s0, s82, 23
	v_bfe_u32 v13, v125, 16, 1
	s_ashr_i32 s1, s0, 31
	v_add3_u32 v13, v125, v13, s90
	s_lshl_b64 s[0:1], s[0:1], 12
	global_store_short_d16_hi v[36:37], v13, off
	v_lshl_add_u64 v[36:37], v[14:15], 0, s[0:1]
	s_or_b32 s0, s75, 24
	v_bfe_u32 v13, v128, 16, 1
	s_ashr_i32 s1, s0, 31
	v_add3_u32 v13, v128, v13, s90
	s_lshl_b64 s[0:1], s[0:1], 12
	global_store_short_d16_hi v[36:37], v13, off
	v_lshl_add_u64 v[36:37], v[14:15], 0, s[0:1]
	s_or_b32 s0, s75, 25
	v_bfe_u32 v13, v129, 16, 1
	s_ashr_i32 s1, s0, 31
	v_add3_u32 v13, v129, v13, s90
	s_lshl_b64 s[0:1], s[0:1], 12
	global_store_short_d16_hi v[36:37], v13, off
	v_lshl_add_u64 v[36:37], v[14:15], 0, s[0:1]
	s_or_b32 s0, s75, 26
	v_bfe_u32 v13, v130, 16, 1
	s_ashr_i32 s1, s0, 31
	v_add3_u32 v13, v130, v13, s90
	s_lshl_b64 s[0:1], s[0:1], 12
	global_store_short_d16_hi v[36:37], v13, off
	v_lshl_add_u64 v[36:37], v[14:15], 0, s[0:1]
	s_or_b32 s0, s75, 27
	v_bfe_u32 v13, v131, 16, 1
	s_ashr_i32 s1, s0, 31
	v_add3_u32 v13, v131, v13, s90
	s_lshl_b64 s[0:1], s[0:1], 12
	global_store_short_d16_hi v[36:37], v13, off
	v_lshl_add_u64 v[36:37], v[14:15], 0, s[0:1]
	s_or_b32 s0, s75, 28
	v_bfe_u32 v13, v132, 16, 1
	s_ashr_i32 s1, s0, 31
	v_add3_u32 v13, v132, v13, s90
	s_lshl_b64 s[0:1], s[0:1], 12
	global_store_short_d16_hi v[36:37], v13, off
	v_lshl_add_u64 v[36:37], v[14:15], 0, s[0:1]
	s_or_b32 s0, s75, 29
	v_bfe_u32 v13, v133, 16, 1
	s_ashr_i32 s1, s0, 31
	v_add3_u32 v13, v133, v13, s90
	s_lshl_b64 s[0:1], s[0:1], 12
	global_store_short_d16_hi v[36:37], v13, off
	v_lshl_add_u64 v[36:37], v[14:15], 0, s[0:1]
	s_or_b32 s0, s75, 30
	v_bfe_u32 v13, v134, 16, 1
	s_ashr_i32 s1, s0, 31
	v_add3_u32 v13, v134, v13, s90
	s_lshl_b64 s[0:1], s[0:1], 12
	global_store_short_d16_hi v[36:37], v13, off
	v_bfe_u32 v13, v135, 16, 1
	v_lshl_add_u64 v[36:37], v[14:15], 0, s[0:1]
	s_or_b32 s0, s75, 31
	v_add3_u32 v13, v135, v13, s90
	s_ashr_i32 s1, s0, 31
	global_store_short_d16_hi v[36:37], v13, off
	v_bfe_u32 v13, v91, 16, 1
	s_lshl_b64 s[0:1], s[0:1], 12
	v_add3_u32 v13, v91, v13, s90
	v_lshl_add_u64 v[14:15], v[14:15], 0, s[0:1]
	global_store_short_d16_hi v[14:15], v13, off
	s_waitcnt lgkmcnt(0)
	s_barrier
	s_mov_b32 s75, s92
	s_cbranch_vccz .LBB0_293
